# attention tile loop rescheduled: QK0, SM0||QK1, SM1||PV interleave with prefetched LDS fragments
# speedup vs baseline: 1.0442x; 1.0442x over previous
; DI void attn_item(const Params& p, char* smem, u16* qbase, const u16* gabase, const u16* kbase, const u16* vtbase,
;                   int tkv, int nkt, int mylimit, const float* lam_p, const int g_wave) {
;     ...
;   unsigned kso[2], vso[2];
; #pragma unroll
;   for (int i = 0; i < 2; ++i) {
;     const int krow = 4 * (2 * wid + i) + (lane >> 4), kpos = lane & 15;
;     kso[i] = (unsigned)(krow * 1024 + ((kpos ^ (krow & 15)) * 8)) * 2u;
;     const int vrow = 8 * (2 * wid + i) + (lane >> 3), vpos = lane & 7;
;     vso[i] = (unsigned)(vrow * tkv + ((vpos ^ ((vrow >> 1) & 7)) * 8)) * 2u;
;   }
;     ...
;   f32x16 O0[4], O1[4];
; #pragma unroll
;   for (int d = 0; d < 4; ++d) { O0[d] = f32x16{}; O1[d] = f32x16{}; }
;   float l0 = 0.f, l1 = 0.f, m0 = -1e30f, m1 = -1e30f;
;     ...
;   STAGE_KV(0, 0);
;   asm volatile("s_waitcnt vmcnt(0)" ::: "memory");
;   __syncthreads();
.LBB0_708:
	s_lshl_b64 s[42:43], s[42:43], 10
	s_add_i32 s82, s82, 4
	s_and_b64 s[34:35], s[54:55], exec
	s_cselect_b32 s34, s82, 17
	s_add_u32 s54, s66, s51
	v_lshrrev_b32_e32 v6, 3, v2
	s_addc_u32 s55, s67, 0
	s_lshl_b32 s35, s80, 1
	v_lshl_add_u32 v7, s80, 3, v5
	v_lshl_or_b32 v9, s80, 4, v6
	v_xor_b32_e32 v11, v5, v4
	v_xor_b32_e32 v8, v7, v4
	v_mul_lo_u32 v10, v9, s79
	v_lshlrev_b32_e32 v11, 3, v11
	s_or_b32 s35, s35, 1
	v_lshlrev_b32_e32 v8, 4, v8
	v_and_or_b32 v10, v11, 56, v10
	v_lshl_add_u32 v11, s35, 2, v5
	v_lshl_or_b32 v6, s35, 3, v6
	s_lshl_b32 s35, s80, 11
	v_and_b32_e32 v8, 0xf0, v8
	v_xor_b32_e32 v12, v11, v4
	v_mul_lo_u32 v13, v6, s79
	v_lshrrev_b32_e32 v6, 1, v6
	s_add_i32 s35, s35, 16
	v_lshl_or_b32 v7, v7, 11, v8
	v_lshlrev_b32_e32 v12, 4, v12
	v_xor_b32_e32 v14, v6, v4
	s_mov_b32 m0, s35
	v_lshlrev_b32_e32 v10, 1, v10
	v_and_b32_e32 v12, 0xf0, v12
	v_lshlrev_b32_e32 v14, 3, v14
	global_load_lds_dwordx4 v7, s[54:55]
	s_add_i32 m0, s35, 0x8000
	v_lshl_or_b32 v11, v11, 11, v12
	v_and_or_b32 v13, v14, 56, v13
	global_load_lds_dwordx4 v10, s[76:77]
	s_add_i32 m0, s35, 0x400
	v_lshlrev_b32_e32 v13, 1, v13
	global_load_lds_dwordx4 v11, s[54:55]
	s_add_i32 m0, s35, 0x8400
	v_and_b32_e32 v7, 31, v4
	global_load_lds_dwordx4 v13, s[76:77]
	v_lshlrev_b32_e32 v10, 3, v4
	v_and_b32_e32 v182, 0x70, v10
	v_mul_u32_u24_e32 v10, 0x110, v7
	v_lshlrev_b32_e32 v7, 7, v7
	s_add_u32 s54, s76, 0x80
	v_lshrrev_b32_e32 v2, 5, v2
	v_add_u32_e32 v11, 16, v7
	s_addc_u32 s55, s77, 0
	s_lshl_b32 s76, s79, 1
	v_lshlrev_b32_e32 v185, 4, v2
	v_add_u32_e32 v198, v11, v7
	v_lshl_add_u32 v206, v2, 3, v11
	v_mul_lo_u32 v2, s76, v9
	v_bitop3_b32 v7, v5, 7, v4 bitop3:0x48
	v_lshl_add_u32 v2, v7, 4, v2
	v_lshl_add_u64 v[188:189], s[54:55], 0, v[2:3]
	v_or_b32_e32 v2, 8, v9
	s_and_b32 s50, s50, 7
	v_mul_lo_u32 v2, s76, v2
	v_bitop3_b32 v4, v6, 7, v4 bitop3:0x48
	s_lshl_b32 s50, s50, 8
	v_lshl_add_u32 v2, v4, 4, v2
	s_add_u32 s50, s66, s50
	v_lshl_add_u64 v[190:191], s[54:55], 0, v[2:3]
	v_lshlrev_b32_e32 v2, 11, v5
	s_addc_u32 s55, s67, 0
	v_lshl_add_u32 v4, s80, 14, v2
	s_add_u32 s54, s50, 0x20000
	v_or_b32_e32 v2, v4, v8
	s_addc_u32 s55, s55, 0
	v_lshl_add_u64 v[192:193], s[54:55], 0, v[2:3]
	v_or_b32_e32 v2, v4, v12
	s_waitcnt vmcnt(0)
	v_add_u32_e32 v2, 0x2000, v2
	v_mov_b32_e32 v16, v3
	v_mov_b32_e32 v17, v3
	v_add3_u32 v205, s81, v10, v185
	v_lshl_add_u64 v[194:195], s[54:55], 0, v[2:3]
	v_mov_b32_e32 v2, v3
	v_mov_b32_e32 v4, v3
	v_mov_b32_e32 v5, v3
	v_mov_b32_e32 v6, v3
	v_mov_b32_e32 v7, v3
	v_mov_b32_e32 v8, v3
	v_mov_b32_e32 v9, v3
	v_mov_b32_e32 v10, v3
	v_mov_b32_e32 v11, v3
	v_mov_b32_e32 v12, v3
	v_mov_b32_e32 v13, v3
	v_mov_b32_e32 v14, v3
	v_mov_b32_e32 v15, v3
	v_mov_b64_e32 v[128:129], v[16:17]
	v_mov_b64_e32 v[96:97], v[16:17]
	v_mov_b64_e32 v[64:65], v[16:17]
	v_mov_b64_e32 v[32:33], v[16:17]
	v_mov_b64_e32 v[144:145], v[16:17]
	v_mov_b64_e32 v[112:113], v[16:17]
	v_mov_b64_e32 v[80:81], v[16:17]
	v_mov_b64_e32 v[48:49], v[16:17]
	v_xor_b32_e32 v199, v184, v185
	s_mov_b32 s50, 0
	v_mov_b32_e32 v207, 0xf149f2ca
	v_mov_b32_e32 v186, 0
	v_mov_b64_e32 v[126:127], v[14:15]
	v_mov_b64_e32 v[124:125], v[12:13]
	v_mov_b64_e32 v[122:123], v[10:11]
	v_mov_b64_e32 v[120:121], v[8:9]
	v_mov_b64_e32 v[118:119], v[6:7]
	v_mov_b64_e32 v[116:117], v[4:5]
	v_mov_b64_e32 v[114:115], v[2:3]
	v_mov_b64_e32 v[94:95], v[14:15]
	v_mov_b64_e32 v[92:93], v[12:13]
	v_mov_b64_e32 v[90:91], v[10:11]
	v_mov_b64_e32 v[88:89], v[8:9]
	v_mov_b64_e32 v[86:87], v[6:7]
	v_mov_b64_e32 v[84:85], v[4:5]
	v_mov_b64_e32 v[82:83], v[2:3]
	v_mov_b64_e32 v[62:63], v[14:15]
	v_mov_b64_e32 v[60:61], v[12:13]
	v_mov_b64_e32 v[58:59], v[10:11]
	v_mov_b64_e32 v[56:57], v[8:9]
	v_mov_b64_e32 v[54:55], v[6:7]
	v_mov_b64_e32 v[52:53], v[4:5]
	v_mov_b64_e32 v[50:51], v[2:3]
	v_mov_b64_e32 v[30:31], v[14:15]
	v_mov_b64_e32 v[28:29], v[12:13]
	v_mov_b64_e32 v[26:27], v[10:11]
	v_mov_b64_e32 v[24:25], v[8:9]
	v_mov_b64_e32 v[22:23], v[6:7]
	v_mov_b64_e32 v[20:21], v[4:5]
	v_mov_b64_e32 v[18:19], v[2:3]
	v_mov_b64_e32 v[142:143], v[14:15]
	v_mov_b64_e32 v[140:141], v[12:13]
	v_mov_b64_e32 v[138:139], v[10:11]
	v_mov_b64_e32 v[136:137], v[8:9]
	v_mov_b64_e32 v[134:135], v[6:7]
	v_mov_b64_e32 v[132:133], v[4:5]
	v_mov_b64_e32 v[130:131], v[2:3]
	v_mov_b64_e32 v[110:111], v[14:15]
	v_mov_b64_e32 v[108:109], v[12:13]
	v_mov_b64_e32 v[106:107], v[10:11]
	v_mov_b64_e32 v[104:105], v[8:9]
	v_mov_b64_e32 v[102:103], v[6:7]
	v_mov_b64_e32 v[100:101], v[4:5]
	v_mov_b64_e32 v[98:99], v[2:3]
	v_mov_b64_e32 v[78:79], v[14:15]
	v_mov_b64_e32 v[76:77], v[12:13]
	v_mov_b64_e32 v[74:75], v[10:11]
	v_mov_b64_e32 v[72:73], v[8:9]
	v_mov_b64_e32 v[70:71], v[6:7]
	v_mov_b64_e32 v[68:69], v[4:5]
	v_mov_b64_e32 v[66:67], v[2:3]
	v_mov_b64_e32 v[46:47], v[14:15]
	v_mov_b64_e32 v[44:45], v[12:13]
	v_mov_b64_e32 v[42:43], v[10:11]
	v_mov_b64_e32 v[40:41], v[8:9]
	v_mov_b64_e32 v[38:39], v[6:7]
	v_mov_b64_e32 v[36:37], v[4:5]
	v_mov_b64_e32 v[34:35], v[2:3]
	v_mov_b32_e32 v187, 0
	v_mov_b32_e32 v2, 0xf149f2ca
	s_mov_b32 s55, 0
	s_movk_i32 s79, 0x60
	s_movk_i32 s80, 0x80
	s_movk_i32 s81, 0xa0
	s_movk_i32 s82, 0xc0
	s_movk_i32 s83, 0xe0
	s_movk_i32 s32, 0x50
	s_movk_i32 s85, 0x70
	s_waitcnt vmcnt(0) lgkmcnt(0)
	s_barrier
	s_add_i32 s54, s55, 1
	s_cmp_ge_u32 s54, s34
	s_cbranch_scc1 .LBB0_711
	s_branch .LBB0_710

; DI void attn_item(const Params& p, char* smem, u16* qbase, const u16* gabase, const u16* kbase, const u16* vtbase,
;                   int tkv, int nkt, int mylimit, const float* lam_p, const int g_wave) {
;     ...
;     if (kt < mylimit) {
;       const char* Kt = Kb + (kt & 1) * KBUF;
;       const char* Vt = Vb + (kt & 1) * VBUF;
;       int zq = 0, kz = (r & 15) * 16, vz = ((r >> 1) & 7) * 16;
;       asm volatile("" : "+v"(zq), "+v"(kz), "+v"(vz));
;       const char* Qk = Qs + zq;
;       bf16x8 pf0[4], pf1[4];
;       SOFTMAX_COMP(0, l0, m0, O0, pf0);
.LBB0_711:
	s_cmp_ge_u32 s55, s78
	s_cbranch_scc1 .LBB0_717
	s_and_b32 s55, s50, 0x4000
	v_add_u32_e32 v16, s55, v198
	v_add_u32_e32 v216, v199, v16
	ds_read_b128 v[220:223], v216
	ds_read_b128 v[224:227], v216 offset:8192
	ds_read_b128 v[228:231], v205
	v_xad_u32 v217, v199, 32, v16
	ds_read_b128 v[232:235], v217
	ds_read_b128 v[236:239], v217 offset:8192
	ds_read_b128 v[240:243], v205 offset:32
	v_xad_u32 v216, v199, 64, v16
	ds_read_b128 v[244:247], v216
	ds_read_b128 v[248:251], v216 offset:8192
	ds_read_b128 v[200:203], v205 offset:64
	v_xad_u32 v217, v199, s79, v16
	ds_read_b128 v[208:211], v217
	ds_read_b128 v[212:215], v217 offset:8192
	s_waitcnt lgkmcnt(8)
	v_mfma_f32_32x32x16_bf16 v[162:177], v[220:223], v[228:231], 0
	v_mfma_f32_32x32x16_bf16 v[146:161], v[224:227], v[228:231], 0
	ds_read_b128 v[220:223], v205 offset:96
	s_waitcnt lgkmcnt(6)
	v_mfma_f32_32x32x16_bf16 v[162:177], v[232:235], v[240:243], v[162:177]
	v_mfma_f32_32x32x16_bf16 v[146:161], v[236:239], v[240:243], v[146:161]
	s_waitcnt lgkmcnt(3)
	v_mfma_f32_32x32x16_bf16 v[162:177], v[244:247], v[200:203], v[162:177]
	v_mfma_f32_32x32x16_bf16 v[146:161], v[248:251], v[200:203], v[146:161]
	s_waitcnt lgkmcnt(0)
	v_mfma_f32_32x32x16_bf16 v[162:177], v[208:211], v[220:223], v[162:177]
	v_mfma_f32_32x32x16_bf16 v[146:161], v[212:215], v[220:223], v[146:161]
	v_xad_u32 v252, v199, s80, v16
	ds_read_b128 v[200:203], v252
	ds_read_b128 v[208:211], v252 offset:8192
	ds_read_b128 v[212:215], v205 offset:128
	s_nop 7
	v_max3_f32 v17, v162, v163, v164
	v_max3_f32 v219, v146, v147, v148
	v_max3_f32 v17, v17, v165, v166
	v_max3_f32 v219, v219, v149, v150
	v_max3_f32 v17, v17, v167, v168
	v_max3_f32 v219, v219, v151, v152
	v_max3_f32 v17, v17, v169, v170
	v_max3_f32 v219, v219, v153, v154
	v_max3_f32 v17, v17, v171, v172
	v_max3_f32 v219, v219, v155, v156
	v_max3_f32 v17, v17, v173, v174
	v_max3_f32 v219, v219, v157, v158
	v_max3_f32 v17, v17, v175, v176
	v_max3_f32 v219, v219, v159, v160
	v_max_f32_e32 v219, v219, v161
	v_max3_f32 v17, v17, v177, v219
	s_waitcnt lgkmcnt(0)
	v_mfma_f32_32x32x16_bf16 v[220:235], v[200:203], v[212:215], 0
	v_mfma_f32_32x32x16_bf16 v[236:251], v[208:211], v[212:215], 0
	v_xad_u32 v253, v199, s81, v16
	ds_read_b128 v[200:203], v253
	ds_read_b128 v[208:211], v253 offset:8192
	ds_read_b128 v[212:215], v205 offset:160
	v_mov_b32_e32 v219, v17
	s_nop 1
	v_permlane32_swap_b32_e32 v17, v219
	v_max_f32_e32 v17, v17, v219
	v_mul_f32_e32 v17, s97, v17
	v_add_f32_e32 v219, 0x41000000, v207
	v_cmp_le_f32_e32 vcc, v17, v219
	s_cmp_eq_u64 vcc, exec
	s_cbranch_scc1 .Lat_nr0
	v_max_f32_e32 v219, v207, v17
	v_sub_f32_e32 v216, v207, v219
	v_exp_f32_e32 v216, v216
	v_mov_b32_e32 v207, v219
	s_nop 0
	v_pk_mul_f32 v[144:145], v[144:145], v[216:217] op_sel_hi:[1,0]
	v_pk_mul_f32 v[142:143], v[142:143], v[216:217] op_sel_hi:[1,0]
	v_pk_mul_f32 v[140:141], v[140:141], v[216:217] op_sel_hi:[1,0]
	v_pk_mul_f32 v[138:139], v[138:139], v[216:217] op_sel_hi:[1,0]
	v_pk_mul_f32 v[136:137], v[136:137], v[216:217] op_sel_hi:[1,0]
	v_pk_mul_f32 v[134:135], v[134:135], v[216:217] op_sel_hi:[1,0]
	v_pk_mul_f32 v[132:133], v[132:133], v[216:217] op_sel_hi:[1,0]
	v_pk_mul_f32 v[130:131], v[130:131], v[216:217] op_sel_hi:[1,0]
	v_pk_mul_f32 v[112:113], v[112:113], v[216:217] op_sel_hi:[1,0]
	v_pk_mul_f32 v[110:111], v[110:111], v[216:217] op_sel_hi:[1,0]
	v_pk_mul_f32 v[108:109], v[108:109], v[216:217] op_sel_hi:[1,0]
	v_pk_mul_f32 v[106:107], v[106:107], v[216:217] op_sel_hi:[1,0]
	v_pk_mul_f32 v[104:105], v[104:105], v[216:217] op_sel_hi:[1,0]
	v_pk_mul_f32 v[102:103], v[102:103], v[216:217] op_sel_hi:[1,0]
	v_pk_mul_f32 v[100:101], v[100:101], v[216:217] op_sel_hi:[1,0]
	v_pk_mul_f32 v[98:99], v[98:99], v[216:217] op_sel_hi:[1,0]
	v_pk_mul_f32 v[80:81], v[80:81], v[216:217] op_sel_hi:[1,0]
	v_pk_mul_f32 v[78:79], v[78:79], v[216:217] op_sel_hi:[1,0]
	v_pk_mul_f32 v[76:77], v[76:77], v[216:217] op_sel_hi:[1,0]
	v_pk_mul_f32 v[74:75], v[74:75], v[216:217] op_sel_hi:[1,0]
	v_pk_mul_f32 v[72:73], v[72:73], v[216:217] op_sel_hi:[1,0]
	v_pk_mul_f32 v[70:71], v[70:71], v[216:217] op_sel_hi:[1,0]
	v_pk_mul_f32 v[68:69], v[68:69], v[216:217] op_sel_hi:[1,0]
	v_pk_mul_f32 v[66:67], v[66:67], v[216:217] op_sel_hi:[1,0]
	v_pk_mul_f32 v[48:49], v[48:49], v[216:217] op_sel_hi:[1,0]
	v_pk_mul_f32 v[46:47], v[46:47], v[216:217] op_sel_hi:[1,0]
	v_pk_mul_f32 v[44:45], v[44:45], v[216:217] op_sel_hi:[1,0]
	v_pk_mul_f32 v[42:43], v[42:43], v[216:217] op_sel_hi:[1,0]
	v_pk_mul_f32 v[40:41], v[40:41], v[216:217] op_sel_hi:[1,0]
	v_pk_mul_f32 v[38:39], v[38:39], v[216:217] op_sel_hi:[1,0]
	v_pk_mul_f32 v[36:37], v[36:37], v[216:217] op_sel_hi:[1,0]
	v_pk_mul_f32 v[34:35], v[34:35], v[216:217] op_sel_hi:[1,0]
	v_mul_f32_e32 v186, v186, v216
; DI void attn_item(const Params& p, char* smem, u16* qbase, const u16* gabase, const u16* kbase, const u16* vtbase,
;                   int tkv, int nkt, int mylimit, const float* lam_p, const int g_wave) {
;     ...
; #pragma unroll
;       for (int d = 0; d < 4; ++d) {
;         const int vrow = 32 * d + r;
; #pragma unroll
;         for (int sp = 0; sp < 4; ++sp) {
;           const u32x2 lo = *(const u32x2*)(Vt + vrow * 128 + ((32 * sp) ^ vz) + 8 * hh);
;           const u32x2 hi = *(const u32x2*)(Vt + vrow * 128 + ((32 * sp + 16) ^ vz) + 8 * hh);
;           u32x4 w = {lo[0], lo[1], hi[0], hi[1]};
;           const bf16x8 vf = *reinterpret_cast<bf16x8*>(&w);
;           O0[d] = __builtin_amdgcn_mfma_f32_32x32x16_bf16(vf, pf0[sp], O0[d], 0, 0, 0);
;           O1[d] = __builtin_amdgcn_mfma_f32_32x32x16_bf16(vf, pf1[sp], O1[d], 0, 0, 0);
.Lat_nr0:
	v_fma_f32 v162, v162, s97, -v207
	v_fma_f32 v163, v163, s97, -v207
	v_fma_f32 v164, v164, s97, -v207
	v_fma_f32 v165, v165, s97, -v207
	v_fma_f32 v166, v166, s97, -v207
	v_fma_f32 v167, v167, s97, -v207
	v_fma_f32 v168, v168, s97, -v207
	v_fma_f32 v169, v169, s97, -v207
	v_exp_f32_e32 v162, v162
	v_exp_f32_e32 v163, v163
	v_exp_f32_e32 v164, v164
	v_exp_f32_e32 v165, v165
	v_exp_f32_e32 v166, v166
	v_exp_f32_e32 v167, v167
	v_exp_f32_e32 v168, v168
	v_exp_f32_e32 v169, v169
	s_waitcnt lgkmcnt(0)
	v_mfma_f32_32x32x16_bf16 v[220:235], v[200:203], v[212:215], v[220:235]
	v_mfma_f32_32x32x16_bf16 v[236:251], v[208:211], v[212:215], v[236:251]
	v_xad_u32 v252, v199, s82, v16
	ds_read_b128 v[200:203], v252
	ds_read_b128 v[208:211], v252 offset:8192
	ds_read_b128 v[212:215], v205 offset:192
	v_fma_f32 v170, v170, s97, -v207
	v_fma_f32 v171, v171, s97, -v207
	v_fma_f32 v172, v172, s97, -v207
	v_fma_f32 v173, v173, s97, -v207
	v_fma_f32 v174, v174, s97, -v207
	v_fma_f32 v175, v175, s97, -v207
	v_fma_f32 v176, v176, s97, -v207
	v_fma_f32 v177, v177, s97, -v207
	v_cvt_pk_bf16_f32 v178, v162, v163
	v_cvt_pk_bf16_f32 v179, v164, v165
	v_cvt_pk_bf16_f32 v180, v166, v167
	v_cvt_pk_bf16_f32 v181, v168, v169
	v_exp_f32_e32 v170, v170
	v_exp_f32_e32 v171, v171
	v_exp_f32_e32 v172, v172
	v_exp_f32_e32 v173, v173
	v_exp_f32_e32 v174, v174
	v_exp_f32_e32 v175, v175
	v_exp_f32_e32 v176, v176
	v_exp_f32_e32 v177, v177
	v_mov_b32_e32 v17, v162
	v_mov_b32_e32 v219, v163
	v_add_f32_e32 v17, v164, v17
	v_add_f32_e32 v219, v165, v219
	v_add_f32_e32 v17, v166, v17
	v_add_f32_e32 v219, v167, v219
	v_add_f32_e32 v17, v168, v17
	v_add_f32_e32 v219, v169, v219
	s_waitcnt lgkmcnt(0)
	v_mfma_f32_32x32x16_bf16 v[220:235], v[200:203], v[212:215], v[220:235]
	v_mfma_f32_32x32x16_bf16 v[236:251], v[208:211], v[212:215], v[236:251]
	v_xad_u32 v253, v199, s83, v16
	ds_read_b128 v[200:203], v253
	ds_read_b128 v[208:211], v253 offset:8192
	ds_read_b128 v[212:215], v205 offset:224
	v_fma_f32 v146, v146, s97, -v207
	v_fma_f32 v147, v147, s97, -v207
	v_fma_f32 v148, v148, s97, -v207
	v_fma_f32 v149, v149, s97, -v207
	v_fma_f32 v150, v150, s97, -v207
	v_fma_f32 v151, v151, s97, -v207
	v_fma_f32 v152, v152, s97, -v207
	v_fma_f32 v153, v153, s97, -v207
	v_cvt_pk_bf16_f32 v12, v170, v171
	v_cvt_pk_bf16_f32 v13, v172, v173
	v_cvt_pk_bf16_f32 v14, v174, v175
	v_cvt_pk_bf16_f32 v15, v176, v177
	v_exp_f32_e32 v146, v146
	v_exp_f32_e32 v147, v147
	v_exp_f32_e32 v148, v148
	v_exp_f32_e32 v149, v149
	v_exp_f32_e32 v150, v150
	v_exp_f32_e32 v151, v151
	v_exp_f32_e32 v152, v152
	v_exp_f32_e32 v153, v153
	v_add_f32_e32 v17, v170, v17
	v_add_f32_e32 v219, v171, v219
	v_add_f32_e32 v17, v172, v17
	v_add_f32_e32 v219, v173, v219
	v_add_f32_e32 v17, v174, v17
	v_add_f32_e32 v219, v175, v219
	v_add_f32_e32 v17, v176, v17
	v_add_f32_e32 v219, v177, v219
	s_waitcnt lgkmcnt(0)
	v_mfma_f32_32x32x16_bf16 v[220:235], v[200:203], v[212:215], v[220:235]
	v_mfma_f32_32x32x16_bf16 v[236:251], v[208:211], v[212:215], v[236:251]
	v_fma_f32 v154, v154, s97, -v207
	v_fma_f32 v155, v155, s97, -v207
	v_fma_f32 v156, v156, s97, -v207
	v_fma_f32 v157, v157, s97, -v207
	v_fma_f32 v158, v158, s97, -v207
	v_fma_f32 v159, v159, s97, -v207
	v_fma_f32 v160, v160, s97, -v207
	v_fma_f32 v161, v161, s97, -v207
	v_cvt_pk_bf16_f32 v8, v146, v147
	v_cvt_pk_bf16_f32 v9, v148, v149
	v_cvt_pk_bf16_f32 v10, v150, v151
	v_cvt_pk_bf16_f32 v11, v152, v153
	v_exp_f32_e32 v154, v154
	v_exp_f32_e32 v155, v155
	v_exp_f32_e32 v156, v156
	v_exp_f32_e32 v157, v157
	v_exp_f32_e32 v158, v158
	v_exp_f32_e32 v159, v159
	v_exp_f32_e32 v160, v160
	v_exp_f32_e32 v161, v161
	v_add_f32_e32 v17, v146, v17
	v_add_f32_e32 v219, v147, v219
	v_add_f32_e32 v17, v148, v17
	v_add_f32_e32 v219, v149, v219
	v_add_f32_e32 v17, v150, v17
	v_add_f32_e32 v219, v151, v219
	v_add_f32_e32 v17, v152, v17
	v_add_f32_e32 v219, v153, v219
	v_cvt_pk_bf16_f32 v4, v154, v155
	v_cvt_pk_bf16_f32 v5, v156, v157
	v_cvt_pk_bf16_f32 v6, v158, v159
	v_cvt_pk_bf16_f32 v7, v160, v161
	v_add_f32_e32 v17, v154, v17
	v_add_f32_e32 v219, v155, v219
	v_add_f32_e32 v17, v156, v17
	v_add_f32_e32 v219, v157, v219
	v_add_f32_e32 v17, v158, v17
	v_add_f32_e32 v219, v159, v219
	v_add_f32_e32 v17, v160, v17
	v_add_f32_e32 v219, v161, v219
	v_add_f32_e32 v17, v17, v219
	v_add_f32_e32 v186, v186, v17
	v_add_u32_e32 v16, s55, v206
	v_add_u32_e32 v200, v182, v16
	v_xad_u32 v201, v182, 16, v16
	v_xad_u32 v202, v182, 32, v16
	v_xad_u32 v203, v182, 48, v16
	v_xad_u32 v208, v182, 64, v16
	v_xad_u32 v209, v182, s32, v16
	v_xad_u32 v210, v182, s79, v16
	v_xad_u32 v211, v182, s85, v16
	ds_read_b64 v[162:163], v200 offset:32768
	ds_read_b64 v[164:165], v201 offset:32768
	ds_read_b64 v[166:167], v200 offset:36864
	ds_read_b64 v[168:169], v201 offset:36864
	ds_read_b64 v[170:171], v200 offset:40960
	ds_read_b64 v[172:173], v201 offset:40960
	ds_read_b64 v[174:175], v200 offset:45056
	ds_read_b64 v[176:177], v201 offset:45056
	v_max3_f32 v17, v220, v221, v222
	v_max3_f32 v219, v236, v237, v238
	v_max3_f32 v17, v17, v223, v224
	v_max3_f32 v219, v219, v239, v240
	v_max3_f32 v17, v17, v225, v226
	v_max3_f32 v219, v219, v241, v242
	v_max3_f32 v17, v17, v227, v228
	v_max3_f32 v219, v219, v243, v244
	s_waitcnt lgkmcnt(6)
	v_mfma_f32_32x32x16_bf16 v[130:145], v[162:165], v[178:181], v[130:145]
	v_max3_f32 v17, v17, v229, v230
	v_max3_f32 v219, v219, v245, v246
	v_max3_f32 v17, v17, v231, v232
	v_max3_f32 v219, v219, v247, v248
	v_max3_f32 v17, v17, v233, v234
	v_max3_f32 v219, v219, v249, v250
	v_max_f32_e32 v219, v219, v251
	v_max3_f32 v17, v17, v235, v219
	s_waitcnt lgkmcnt(4)
	v_mfma_f32_32x32x16_bf16 v[98:113], v[166:169], v[178:181], v[98:113]
	v_mov_b32_e32 v219, v17
	s_nop 1
	v_permlane32_swap_b32_e32 v17, v219
	v_max_f32_e32 v17, v17, v219
	v_mul_f32_e32 v17, s97, v17
	v_add_f32_e32 v219, 0x41000000, v2
	v_cmp_le_f32_e32 vcc, v17, v219
	s_cmp_eq_u64 vcc, exec
	s_cbranch_scc1 .Lat_nr1
	v_max_f32_e32 v219, v2, v17
	v_sub_f32_e32 v216, v2, v219
	v_exp_f32_e32 v216, v216
	v_mov_b32_e32 v2, v219
	s_nop 0
	v_pk_mul_f32 v[128:129], v[128:129], v[216:217] op_sel_hi:[1,0]
	v_pk_mul_f32 v[126:127], v[126:127], v[216:217] op_sel_hi:[1,0]
	v_pk_mul_f32 v[124:125], v[124:125], v[216:217] op_sel_hi:[1,0]
	v_pk_mul_f32 v[122:123], v[122:123], v[216:217] op_sel_hi:[1,0]
	v_pk_mul_f32 v[120:121], v[120:121], v[216:217] op_sel_hi:[1,0]
	v_pk_mul_f32 v[118:119], v[118:119], v[216:217] op_sel_hi:[1,0]
	v_pk_mul_f32 v[116:117], v[116:117], v[216:217] op_sel_hi:[1,0]
	v_pk_mul_f32 v[114:115], v[114:115], v[216:217] op_sel_hi:[1,0]
	v_pk_mul_f32 v[96:97], v[96:97], v[216:217] op_sel_hi:[1,0]
	v_pk_mul_f32 v[94:95], v[94:95], v[216:217] op_sel_hi:[1,0]
	v_pk_mul_f32 v[92:93], v[92:93], v[216:217] op_sel_hi:[1,0]
	v_pk_mul_f32 v[90:91], v[90:91], v[216:217] op_sel_hi:[1,0]
	v_pk_mul_f32 v[88:89], v[88:89], v[216:217] op_sel_hi:[1,0]
	v_pk_mul_f32 v[86:87], v[86:87], v[216:217] op_sel_hi:[1,0]
	v_pk_mul_f32 v[84:85], v[84:85], v[216:217] op_sel_hi:[1,0]
	v_pk_mul_f32 v[82:83], v[82:83], v[216:217] op_sel_hi:[1,0]
	v_pk_mul_f32 v[64:65], v[64:65], v[216:217] op_sel_hi:[1,0]
	v_pk_mul_f32 v[62:63], v[62:63], v[216:217] op_sel_hi:[1,0]
	v_pk_mul_f32 v[60:61], v[60:61], v[216:217] op_sel_hi:[1,0]
	v_pk_mul_f32 v[58:59], v[58:59], v[216:217] op_sel_hi:[1,0]
	v_pk_mul_f32 v[56:57], v[56:57], v[216:217] op_sel_hi:[1,0]
	v_pk_mul_f32 v[54:55], v[54:55], v[216:217] op_sel_hi:[1,0]
	v_pk_mul_f32 v[52:53], v[52:53], v[216:217] op_sel_hi:[1,0]
	v_pk_mul_f32 v[50:51], v[50:51], v[216:217] op_sel_hi:[1,0]
	v_pk_mul_f32 v[32:33], v[32:33], v[216:217] op_sel_hi:[1,0]
	v_pk_mul_f32 v[30:31], v[30:31], v[216:217] op_sel_hi:[1,0]
	v_pk_mul_f32 v[28:29], v[28:29], v[216:217] op_sel_hi:[1,0]
	v_pk_mul_f32 v[26:27], v[26:27], v[216:217] op_sel_hi:[1,0]
	v_pk_mul_f32 v[24:25], v[24:25], v[216:217] op_sel_hi:[1,0]
	v_pk_mul_f32 v[22:23], v[22:23], v[216:217] op_sel_hi:[1,0]
	v_pk_mul_f32 v[20:21], v[20:21], v[216:217] op_sel_hi:[1,0]
	v_pk_mul_f32 v[18:19], v[18:19], v[216:217] op_sel_hi:[1,0]
	v_mul_f32_e32 v187, v187, v216
; DI void attn_item(const Params& p, char* smem, u16* qbase, const u16* gabase, const u16* kbase, const u16* vtbase,
;                   int tkv, int nkt, int mylimit, const float* lam_p, const int g_wave) {
;     ...
; #pragma unroll
;       for (int d = 0; d < 4; ++d) {
;         const int vrow = 32 * d + r;
; #pragma unroll
;         for (int sp = 0; sp < 4; ++sp) {
;           const u32x2 lo = *(const u32x2*)(Vt + vrow * 128 + ((32 * sp) ^ vz) + 8 * hh);
;           const u32x2 hi = *(const u32x2*)(Vt + vrow * 128 + ((32 * sp + 16) ^ vz) + 8 * hh);
;           u32x4 w = {lo[0], lo[1], hi[0], hi[1]};
;           const bf16x8 vf = *reinterpret_cast<bf16x8*>(&w);
;           O0[d] = __builtin_amdgcn_mfma_f32_32x32x16_bf16(vf, pf0[sp], O0[d], 0, 0, 0);
;           O1[d] = __builtin_amdgcn_mfma_f32_32x32x16_bf16(vf, pf1[sp], O1[d], 0, 0, 0);
;         }
;         __builtin_amdgcn_sched_barrier(0);
;       }
.Lat_nr1:
	s_waitcnt lgkmcnt(2)
	v_mfma_f32_32x32x16_bf16 v[66:81], v[170:173], v[178:181], v[66:81]
	v_fma_f32 v220, v220, s97, -v2
	v_fma_f32 v221, v221, s97, -v2
	v_fma_f32 v222, v222, s97, -v2
	v_fma_f32 v223, v223, s97, -v2
	v_fma_f32 v224, v224, s97, -v2
	v_fma_f32 v225, v225, s97, -v2
	v_fma_f32 v226, v226, s97, -v2
	v_fma_f32 v227, v227, s97, -v2
	s_waitcnt lgkmcnt(0)
	v_mfma_f32_32x32x16_bf16 v[34:49], v[174:177], v[178:181], v[34:49]
	v_exp_f32_e32 v220, v220
	v_exp_f32_e32 v221, v221
	v_exp_f32_e32 v222, v222
	v_exp_f32_e32 v223, v223
	v_exp_f32_e32 v224, v224
	v_exp_f32_e32 v225, v225
	v_exp_f32_e32 v226, v226
	v_exp_f32_e32 v227, v227
	v_fma_f32 v228, v228, s97, -v2
	v_fma_f32 v229, v229, s97, -v2
	v_fma_f32 v230, v230, s97, -v2
	v_fma_f32 v231, v231, s97, -v2
	v_fma_f32 v232, v232, s97, -v2
	v_fma_f32 v233, v233, s97, -v2
	v_fma_f32 v234, v234, s97, -v2
	v_fma_f32 v235, v235, s97, -v2
	v_cvt_pk_bf16_f32 v146, v220, v221
	v_cvt_pk_bf16_f32 v147, v222, v223
	v_cvt_pk_bf16_f32 v148, v224, v225
	v_cvt_pk_bf16_f32 v149, v226, v227
	s_nop 1
	v_mfma_f32_32x32x16_bf16 v[114:129], v[162:165], v[146:149], v[114:129]
	ds_read_b64 v[162:163], v202 offset:32768
	ds_read_b64 v[164:165], v203 offset:32768
	v_exp_f32_e32 v228, v228
	v_exp_f32_e32 v229, v229
	v_exp_f32_e32 v230, v230
	v_exp_f32_e32 v231, v231
	v_exp_f32_e32 v232, v232
	v_exp_f32_e32 v233, v233
	v_exp_f32_e32 v234, v234
	v_mfma_f32_32x32x16_bf16 v[82:97], v[166:169], v[146:149], v[82:97]
	ds_read_b64 v[166:167], v202 offset:36864
	ds_read_b64 v[168:169], v203 offset:36864
	v_exp_f32_e32 v235, v235
	v_mov_b32_e32 v17, v220
	v_mov_b32_e32 v219, v221
	v_add_f32_e32 v17, v222, v17
	v_add_f32_e32 v219, v223, v219
	v_add_f32_e32 v17, v224, v17
	v_add_f32_e32 v219, v225, v219
	v_mfma_f32_32x32x16_bf16 v[50:65], v[170:173], v[146:149], v[50:65]
	ds_read_b64 v[170:171], v202 offset:40960
	ds_read_b64 v[172:173], v203 offset:40960
	v_add_f32_e32 v17, v226, v17
	v_add_f32_e32 v219, v227, v219
	v_cvt_pk_bf16_f32 v150, v228, v229
	v_cvt_pk_bf16_f32 v151, v230, v231
	v_cvt_pk_bf16_f32 v152, v232, v233
	v_cvt_pk_bf16_f32 v153, v234, v235
	v_fma_f32 v236, v236, s97, -v2
	v_mfma_f32_32x32x16_bf16 v[18:33], v[174:177], v[146:149], v[18:33]
	ds_read_b64 v[174:175], v202 offset:45056
	ds_read_b64 v[176:177], v203 offset:45056
	v_fma_f32 v237, v237, s97, -v2
	v_fma_f32 v238, v238, s97, -v2
	v_fma_f32 v239, v239, s97, -v2
	v_fma_f32 v240, v240, s97, -v2
	v_fma_f32 v241, v241, s97, -v2
	v_fma_f32 v242, v242, s97, -v2
	v_fma_f32 v243, v243, s97, -v2
	s_waitcnt lgkmcnt(6)
	v_mfma_f32_32x32x16_bf16 v[130:145], v[162:165], v[12:15], v[130:145]
	v_mfma_f32_32x32x16_bf16 v[114:129], v[162:165], v[150:153], v[114:129]
	ds_read_b64 v[162:163], v208 offset:32768
	ds_read_b64 v[164:165], v209 offset:32768
	v_exp_f32_e32 v236, v236
	v_exp_f32_e32 v237, v237
	v_exp_f32_e32 v238, v238
	v_exp_f32_e32 v239, v239
	v_exp_f32_e32 v240, v240
	v_exp_f32_e32 v241, v241
	v_exp_f32_e32 v242, v242
	s_waitcnt lgkmcnt(6)
	v_mfma_f32_32x32x16_bf16 v[98:113], v[166:169], v[12:15], v[98:113]
	v_mfma_f32_32x32x16_bf16 v[82:97], v[166:169], v[150:153], v[82:97]
	ds_read_b64 v[166:167], v208 offset:36864
	ds_read_b64 v[168:169], v209 offset:36864
	v_exp_f32_e32 v243, v243
	v_add_f32_e32 v17, v228, v17
	v_add_f32_e32 v219, v229, v219
	v_add_f32_e32 v17, v230, v17
	v_add_f32_e32 v219, v231, v219
	v_add_f32_e32 v17, v232, v17
	v_add_f32_e32 v219, v233, v219
	s_waitcnt lgkmcnt(6)
	v_mfma_f32_32x32x16_bf16 v[66:81], v[170:173], v[12:15], v[66:81]
	v_mfma_f32_32x32x16_bf16 v[50:65], v[170:173], v[150:153], v[50:65]
	ds_read_b64 v[170:171], v208 offset:40960
	ds_read_b64 v[172:173], v209 offset:40960
	v_add_f32_e32 v17, v234, v17
	v_add_f32_e32 v219, v235, v219
	v_cvt_pk_bf16_f32 v154, v236, v237
	v_cvt_pk_bf16_f32 v155, v238, v239
	v_cvt_pk_bf16_f32 v156, v240, v241
	v_cvt_pk_bf16_f32 v157, v242, v243
	v_fma_f32 v244, v244, s97, -v2
	s_waitcnt lgkmcnt(6)
	v_mfma_f32_32x32x16_bf16 v[34:49], v[174:177], v[12:15], v[34:49]
	v_mfma_f32_32x32x16_bf16 v[18:33], v[174:177], v[150:153], v[18:33]
	ds_read_b64 v[174:175], v208 offset:45056
	ds_read_b64 v[176:177], v209 offset:45056
	v_fma_f32 v245, v245, s97, -v2
	v_fma_f32 v246, v246, s97, -v2
	v_fma_f32 v247, v247, s97, -v2
	v_fma_f32 v248, v248, s97, -v2
	v_fma_f32 v249, v249, s97, -v2
	v_fma_f32 v250, v250, s97, -v2
	v_fma_f32 v251, v251, s97, -v2
	s_waitcnt lgkmcnt(6)
	v_mfma_f32_32x32x16_bf16 v[130:145], v[162:165], v[8:11], v[130:145]
	v_mfma_f32_32x32x16_bf16 v[114:129], v[162:165], v[154:157], v[114:129]
	ds_read_b64 v[162:163], v210 offset:32768
	ds_read_b64 v[164:165], v211 offset:32768
	v_exp_f32_e32 v244, v244
	v_exp_f32_e32 v245, v245
	v_exp_f32_e32 v246, v246
	v_exp_f32_e32 v247, v247
	v_exp_f32_e32 v248, v248
	v_exp_f32_e32 v249, v249
	v_exp_f32_e32 v250, v250
	s_waitcnt lgkmcnt(6)
	v_mfma_f32_32x32x16_bf16 v[98:113], v[166:169], v[8:11], v[98:113]
	v_mfma_f32_32x32x16_bf16 v[82:97], v[166:169], v[154:157], v[82:97]
	ds_read_b64 v[166:167], v210 offset:36864
	ds_read_b64 v[168:169], v211 offset:36864
	v_exp_f32_e32 v251, v251
	v_add_f32_e32 v17, v236, v17
	v_add_f32_e32 v219, v237, v219
	v_add_f32_e32 v17, v238, v17
	v_add_f32_e32 v219, v239, v219
	v_add_f32_e32 v17, v240, v17
	v_add_f32_e32 v219, v241, v219
	s_waitcnt lgkmcnt(6)
	v_mfma_f32_32x32x16_bf16 v[66:81], v[170:173], v[8:11], v[66:81]
	v_mfma_f32_32x32x16_bf16 v[50:65], v[170:173], v[154:157], v[50:65]
	ds_read_b64 v[170:171], v210 offset:40960
	ds_read_b64 v[172:173], v211 offset:40960
	v_add_f32_e32 v17, v242, v17
	v_add_f32_e32 v219, v243, v219
	v_cvt_pk_bf16_f32 v158, v244, v245
	v_cvt_pk_bf16_f32 v159, v246, v247
	v_cvt_pk_bf16_f32 v160, v248, v249
	v_cvt_pk_bf16_f32 v161, v250, v251
	v_add_f32_e32 v17, v244, v17
	s_waitcnt lgkmcnt(6)
	v_mfma_f32_32x32x16_bf16 v[34:49], v[174:177], v[8:11], v[34:49]
	v_mfma_f32_32x32x16_bf16 v[18:33], v[174:177], v[154:157], v[18:33]
	ds_read_b64 v[174:175], v210 offset:45056
	ds_read_b64 v[176:177], v211 offset:45056
	v_add_f32_e32 v219, v245, v219
	v_add_f32_e32 v17, v246, v17
	v_add_f32_e32 v219, v247, v219
	v_add_f32_e32 v17, v248, v17
	v_add_f32_e32 v219, v249, v219
	v_add_f32_e32 v17, v250, v17
	v_add_f32_e32 v219, v251, v219
	s_waitcnt lgkmcnt(6)
	v_mfma_f32_32x32x16_bf16 v[130:145], v[162:165], v[4:7], v[130:145]
	v_mfma_f32_32x32x16_bf16 v[114:129], v[162:165], v[158:161], v[114:129]
	v_add_f32_e32 v17, v17, v219
	s_waitcnt lgkmcnt(4)
	v_mfma_f32_32x32x16_bf16 v[98:113], v[166:169], v[4:7], v[98:113]
	v_mfma_f32_32x32x16_bf16 v[82:97], v[166:169], v[158:161], v[82:97]
	v_add_f32_e32 v187, v187, v17
	s_waitcnt lgkmcnt(2)
	v_mfma_f32_32x32x16_bf16 v[66:81], v[170:173], v[4:7], v[66:81]
	v_mfma_f32_32x32x16_bf16 v[50:65], v[170:173], v[158:161], v[50:65]
	s_waitcnt lgkmcnt(0)
	v_mfma_f32_32x32x16_bf16 v[34:49], v[174:177], v[4:7], v[34:49]
	v_mfma_f32_32x32x16_bf16 v[18:33], v[174:177], v[158:161], v[18:33]
